# GEMM K-loops: per-interval s_setprio flips removed, one static s_setprio 1 for the LEAD half (waves 0-3)
# speedup vs baseline: 1.0193x; 1.0036x over previous
.LBB0_127:
	s_ashr_i32 s13, s12, 31
	s_lshl_b64 s[0:1], s[12:13], 19
	s_add_u32 s42, s6, s0
	v_cmp_lt_i64_e32 vcc, s[34:35], v[236:237]
	s_addc_u32 s43, s7, s1
	s_and_b64 s[0:1], vcc, exec
	s_cselect_b32 s0, s43, s19
	s_cselect_b32 s1, s42, s18
	s_ashr_i32 s31, s30, 31
	s_lshl_b64 s[24:25], s[30:31], 19
	s_add_u32 s44, s16, s24
	s_addc_u32 s45, s17, s25
	s_and_b64 s[24:25], vcc, exec
	s_cselect_b32 s13, s45, s15
	s_cselect_b32 s24, s44, s14
	s_add_u32 vcc_lo, s18, 0x40080
	s_addc_u32 vcc_hi, s19, 0
	s_add_u32 s25, s14, 0x100
	v_mov_b32_e32 v0, 0
	s_addc_u32 s31, s15, 0
	s_mov_b32 s34, -2
	v_mov_b32_e32 v1, v0
	v_mov_b32_e32 v2, v0
	v_mov_b32_e32 v3, v0
	v_mov_b32_e32 v4, v0
	v_mov_b32_e32 v5, v0
	v_mov_b32_e32 v6, v0
	v_mov_b32_e32 v7, v0
	v_mov_b32_e32 v16, v0
	v_mov_b32_e32 v17, v0
	v_mov_b32_e32 v18, v0
	v_mov_b32_e32 v19, v0
	v_mov_b32_e32 v20, v0
	v_mov_b32_e32 v21, v0
	v_mov_b32_e32 v22, v0
	v_mov_b32_e32 v23, v0
	v_mov_b32_e32 v32, v0
	v_mov_b32_e32 v33, v0
	v_mov_b32_e32 v34, v0
	v_mov_b32_e32 v35, v0
	v_mov_b32_e32 v36, v0
	v_mov_b32_e32 v37, v0
	v_mov_b32_e32 v38, v0
	v_mov_b32_e32 v39, v0
	v_mov_b32_e32 v48, v0
	v_mov_b32_e32 v49, v0
	v_mov_b32_e32 v50, v0
	v_mov_b32_e32 v51, v0
	v_mov_b32_e32 v52, v0
	v_mov_b32_e32 v53, v0
	v_mov_b32_e32 v54, v0
	v_mov_b32_e32 v55, v0
	v_mov_b32_e32 v8, v0
	v_mov_b32_e32 v9, v0
	v_mov_b32_e32 v10, v0
	v_mov_b32_e32 v11, v0
	v_mov_b32_e32 v12, v0
	v_mov_b32_e32 v13, v0
	v_mov_b32_e32 v14, v0
	v_mov_b32_e32 v15, v0
	v_mov_b32_e32 v24, v0
	v_mov_b32_e32 v25, v0
	v_mov_b32_e32 v26, v0
	v_mov_b32_e32 v27, v0
	v_mov_b32_e32 v28, v0
	v_mov_b32_e32 v29, v0
	v_mov_b32_e32 v30, v0
	v_mov_b32_e32 v31, v0
	v_mov_b32_e32 v40, v0
	v_mov_b32_e32 v41, v0
	v_mov_b32_e32 v42, v0
	v_mov_b32_e32 v43, v0
	v_mov_b32_e32 v44, v0
	v_mov_b32_e32 v45, v0
	v_mov_b32_e32 v46, v0
	v_mov_b32_e32 v47, v0
	v_mov_b32_e32 v56, v0
	v_mov_b32_e32 v57, v0
	v_mov_b32_e32 v58, v0
	v_mov_b32_e32 v59, v0
	v_mov_b32_e32 v60, v0
	v_mov_b32_e32 v61, v0
	v_mov_b32_e32 v62, v0
	v_mov_b32_e32 v63, v0
	v_mov_b32_e32 v64, v0
	v_mov_b32_e32 v65, v0
	v_mov_b32_e32 v66, v0
	v_mov_b32_e32 v67, v0
	v_mov_b32_e32 v68, v0
	v_mov_b32_e32 v69, v0
	v_mov_b32_e32 v70, v0
	v_mov_b32_e32 v71, v0
	v_mov_b32_e32 v80, v0
	v_mov_b32_e32 v81, v0
	v_mov_b32_e32 v82, v0
	v_mov_b32_e32 v83, v0
	v_mov_b32_e32 v84, v0
	v_mov_b32_e32 v85, v0
	v_mov_b32_e32 v86, v0
	v_mov_b32_e32 v87, v0
	v_mov_b32_e32 v96, v0
	v_mov_b32_e32 v97, v0
	v_mov_b32_e32 v98, v0
	v_mov_b32_e32 v99, v0
	v_mov_b32_e32 v100, v0
	v_mov_b32_e32 v101, v0
	v_mov_b32_e32 v102, v0
	v_mov_b32_e32 v103, v0
	v_mov_b32_e32 v112, v0
	v_mov_b32_e32 v113, v0
	v_mov_b32_e32 v114, v0
	v_mov_b32_e32 v115, v0
	v_mov_b32_e32 v116, v0
	v_mov_b32_e32 v117, v0
	v_mov_b32_e32 v118, v0
	v_mov_b32_e32 v119, v0
	v_mov_b32_e32 v72, v0
	v_mov_b32_e32 v73, v0
	v_mov_b32_e32 v74, v0
	v_mov_b32_e32 v75, v0
	v_mov_b32_e32 v76, v0
	v_mov_b32_e32 v77, v0
	v_mov_b32_e32 v78, v0
	v_mov_b32_e32 v79, v0
	v_mov_b32_e32 v88, v0
	v_mov_b32_e32 v89, v0
	v_mov_b32_e32 v90, v0
	v_mov_b32_e32 v91, v0
	v_mov_b32_e32 v92, v0
	v_mov_b32_e32 v93, v0
	v_mov_b32_e32 v94, v0
	v_mov_b32_e32 v95, v0
	v_mov_b32_e32 v104, v0
	v_mov_b32_e32 v105, v0
	v_mov_b32_e32 v106, v0
	v_mov_b32_e32 v107, v0
	v_mov_b32_e32 v108, v0
	v_mov_b32_e32 v109, v0
	v_mov_b32_e32 v110, v0
	v_mov_b32_e32 v111, v0
	v_mov_b32_e32 v120, v0
	v_mov_b32_e32 v121, v0
	v_mov_b32_e32 v122, v0
	v_mov_b32_e32 v123, v0
	v_mov_b32_e32 v124, v0
	v_mov_b32_e32 v125, v0
	v_mov_b32_e32 v126, v0
	v_mov_b32_e32 v127, v0
	s_cmpk_gt_u32 s50, 0xff
	s_cbranch_scc0 .Lgout_leadp
	s_barrier
	s_branch .Lgout_enter
.Lgout_leadp:
	s_setprio 1

.Lgout_epi:
	s_setprio 0
	s_nop 0
	s_nop 0
	s_nop 0
	s_nop 0
	s_nop 0
	s_cmp_lt_i32 s8, 0
	s_cselect_b64 s[14:15], -1, 0
	s_cmp_gt_i32 s8, -1
	s_cbranch_scc1 .LBB0_131
	v_mul_f32_e32 v131, 0x3d372713, v120
	v_mul_f32_e32 v131, v120, v131
	v_fma_f32 v131, v120, v131, v120
	v_mul_f32_e32 v131, 0x3fcc422a, v131
	v_mul_f32_e32 v131, 0xbfb8aa3b, v131
	v_exp_f32_e32 v131, v131
	v_mul_f32_e32 v130, 0x3d372713, v124
	v_mul_f32_e32 v130, v124, v130
	v_fma_f32 v130, v124, v130, v124
	v_add_f32_e32 v131, 1.0, v131
	v_rcp_f32_e32 v132, v131
	v_mul_f32_e32 v131, 0x3d372713, v125
	v_mul_f32_e32 v131, v125, v131
	v_fma_f32 v131, v125, v131, v125
	v_mul_f32_e32 v130, 0x3fcc422a, v130
	v_mul_f32_e32 v131, 0x3fcc422a, v131
	v_mul_f32_e32 v130, 0xbfb8aa3b, v130
	v_mul_f32_e32 v131, 0xbfb8aa3b, v131
	v_mul_f32_e32 v135, 0x3d372713, v122
	v_exp_f32_e32 v130, v130
	v_exp_f32_e32 v131, v131
	v_mul_f32_e32 v135, v122, v135
	v_fma_f32 v135, v122, v135, v122
	v_mul_f32_e32 v135, 0x3fcc422a, v135
	v_mul_f32_e32 v135, 0xbfb8aa3b, v135
	v_add_f32_e32 v130, 1.0, v130
	v_add_f32_e32 v131, 1.0, v131
	v_exp_f32_e32 v135, v135
	v_rcp_f32_e32 v130, v130
	v_rcp_f32_e32 v131, v131
	v_mul_f32_e32 v133, 0x3d372713, v121
	v_add_f32_e32 v135, 1.0, v135
	v_mul_f32_e32 v134, 0x3d372713, v126
	v_rcp_f32_e32 v136, v135
	v_mul_f32_e32 v135, 0x3d372713, v127
	v_pk_mul_f32 v[124:125], v[124:125], v[130:131]
	v_mul_f32_e32 v130, 0x3d372713, v123
	v_mul_f32_e32 v133, v121, v133
	v_mul_f32_e32 v134, v126, v134
	v_mul_f32_e32 v135, v127, v135
	v_mul_f32_e32 v130, v123, v130
	v_fma_f32 v133, v121, v133, v121
	v_fma_f32 v134, v126, v134, v126
	v_fma_f32 v135, v127, v135, v127
	v_fma_f32 v130, v123, v130, v123
	v_mul_f32_e32 v133, 0x3fcc422a, v133
	v_mul_f32_e32 v134, 0x3fcc422a, v134
	v_mul_f32_e32 v135, 0x3fcc422a, v135
	v_mul_f32_e32 v130, 0x3fcc422a, v130
	v_mul_f32_e32 v133, 0xbfb8aa3b, v133
	v_mul_f32_e32 v134, 0xbfb8aa3b, v134
	v_mul_f32_e32 v135, 0xbfb8aa3b, v135
	v_mul_f32_e32 v130, 0xbfb8aa3b, v130
	v_exp_f32_e32 v133, v133
	v_exp_f32_e32 v134, v134
	v_exp_f32_e32 v135, v135
	v_exp_f32_e32 v130, v130
	v_add_f32_e32 v133, 1.0, v133
	v_add_f32_e32 v134, 1.0, v134
	v_add_f32_e32 v135, 1.0, v135
	v_add_f32_e32 v130, 1.0, v130
	v_rcp_f32_e32 v133, v133
	v_rcp_f32_e32 v134, v134
	v_rcp_f32_e32 v135, v135
	v_rcp_f32_e32 v137, v130
	v_pk_mul_f32 v[120:121], v[120:121], v[132:133]
	v_pk_mul_f32 v[126:127], v[126:127], v[134:135]
	v_pk_mul_f32 v[122:123], v[122:123], v[136:137]

.LBB0_270:
	v_lshl_add_u32 v154, s14, 8, v143
	v_readlane_b32 s14, v252, 43
	v_mov_b64_e32 v[0:1], 0x600
	v_ashrrev_i32_e32 v155, 31, v154
	v_readlane_b32 s15, v252, 44
	v_cmp_lt_i64_e32 vcc, s[34:35], v[0:1]
	s_ashr_i32 s13, s12, 31
	v_lshl_add_u64 v[0:1], v[154:155], 2, s[14:15]
	global_load_dword v156, v[0:1], off
	global_load_dword v171, v[0:1], off offset:64
	global_load_dword v170, v[0:1], off offset:128
	global_load_dword v169, v[0:1], off offset:192
	global_load_dword v168, v[0:1], off offset:512
	global_load_dword v167, v[0:1], off offset:576
	global_load_dword v166, v[0:1], off offset:640
	global_load_dword v165, v[0:1], off offset:704
	s_lshl_b64 s[0:1], s[12:13], 19
	v_readlane_b32 s24, v252, 55
	v_readlane_b32 s25, v252, 56
	s_add_u32 s42, s24, s0
	s_addc_u32 s43, s25, s1
	s_and_b64 s[0:1], vcc, exec
	s_cselect_b32 s0, s43, s31
	s_cselect_b32 s1, s42, s30
	s_ashr_i32 s9, s8, 31
	s_lshl_b64 s[24:25], s[8:9], 19
	v_readlane_b32 s34, v252, 41
	v_readlane_b32 s35, v252, 42
	s_add_u32 s44, s34, s24
	s_addc_u32 s45, s35, s25
	s_and_b64 s[24:25], vcc, exec
	s_cselect_b32 s9, s45, s19
	s_cselect_b32 s13, s44, s18
	s_add_u32 s30, s30, 0x40080
	s_addc_u32 s31, s31, 0
	s_add_u32 s17, s18, 0x100
	v_mov_b32_e32 v0, 0
	s_addc_u32 s24, s19, 0
	s_mov_b32 s25, -2
	v_mov_b32_e32 v1, v0
	v_mov_b32_e32 v2, v0
	v_mov_b32_e32 v3, v0
	v_mov_b32_e32 v4, v0
	v_mov_b32_e32 v5, v0
	v_mov_b32_e32 v6, v0
	v_mov_b32_e32 v7, v0
	v_mov_b32_e32 v16, v0
	v_mov_b32_e32 v17, v0
	v_mov_b32_e32 v18, v0
	v_mov_b32_e32 v19, v0
	v_mov_b32_e32 v20, v0
	v_mov_b32_e32 v21, v0
	v_mov_b32_e32 v22, v0
	v_mov_b32_e32 v23, v0
	v_mov_b32_e32 v32, v0
	v_mov_b32_e32 v33, v0
	v_mov_b32_e32 v34, v0
	v_mov_b32_e32 v35, v0
	v_mov_b32_e32 v36, v0
	v_mov_b32_e32 v37, v0
	v_mov_b32_e32 v38, v0
	v_mov_b32_e32 v39, v0
	v_mov_b32_e32 v48, v0
	v_mov_b32_e32 v49, v0
	v_mov_b32_e32 v50, v0
	v_mov_b32_e32 v51, v0
	v_mov_b32_e32 v52, v0
	v_mov_b32_e32 v53, v0
	v_mov_b32_e32 v54, v0
	v_mov_b32_e32 v55, v0
	v_mov_b32_e32 v8, v0
	v_mov_b32_e32 v9, v0
	v_mov_b32_e32 v10, v0
	v_mov_b32_e32 v11, v0
	v_mov_b32_e32 v12, v0
	v_mov_b32_e32 v13, v0
	v_mov_b32_e32 v14, v0
	v_mov_b32_e32 v15, v0
	v_mov_b32_e32 v24, v0
	v_mov_b32_e32 v25, v0
	v_mov_b32_e32 v26, v0
	v_mov_b32_e32 v27, v0
	v_mov_b32_e32 v28, v0
	v_mov_b32_e32 v29, v0
	v_mov_b32_e32 v30, v0
	v_mov_b32_e32 v31, v0
	v_mov_b32_e32 v40, v0
	v_mov_b32_e32 v41, v0
	v_mov_b32_e32 v42, v0
	v_mov_b32_e32 v43, v0
	v_mov_b32_e32 v44, v0
	v_mov_b32_e32 v45, v0
	v_mov_b32_e32 v46, v0
	v_mov_b32_e32 v47, v0
	v_mov_b32_e32 v56, v0
	v_mov_b32_e32 v57, v0
	v_mov_b32_e32 v58, v0
	v_mov_b32_e32 v59, v0
	v_mov_b32_e32 v60, v0
	v_mov_b32_e32 v61, v0
	v_mov_b32_e32 v62, v0
	v_mov_b32_e32 v63, v0
	v_mov_b32_e32 v64, v0
	v_mov_b32_e32 v65, v0
	v_mov_b32_e32 v66, v0
	v_mov_b32_e32 v67, v0
	v_mov_b32_e32 v68, v0
	v_mov_b32_e32 v69, v0
	v_mov_b32_e32 v70, v0
	v_mov_b32_e32 v71, v0
	v_mov_b32_e32 v80, v0
	v_mov_b32_e32 v81, v0
	v_mov_b32_e32 v82, v0
	v_mov_b32_e32 v83, v0
	v_mov_b32_e32 v84, v0
	v_mov_b32_e32 v85, v0
	v_mov_b32_e32 v86, v0
	v_mov_b32_e32 v87, v0
	v_mov_b32_e32 v96, v0
	v_mov_b32_e32 v97, v0
	v_mov_b32_e32 v98, v0
	v_mov_b32_e32 v99, v0
	v_mov_b32_e32 v100, v0
	v_mov_b32_e32 v101, v0
	v_mov_b32_e32 v102, v0
	v_mov_b32_e32 v103, v0
	v_mov_b32_e32 v112, v0
	v_mov_b32_e32 v113, v0
	v_mov_b32_e32 v114, v0
	v_mov_b32_e32 v115, v0
	v_mov_b32_e32 v116, v0
	v_mov_b32_e32 v117, v0
	v_mov_b32_e32 v118, v0
	v_mov_b32_e32 v119, v0
	v_mov_b32_e32 v72, v0
	v_mov_b32_e32 v73, v0
	v_mov_b32_e32 v74, v0
	v_mov_b32_e32 v75, v0
	v_mov_b32_e32 v76, v0
	v_mov_b32_e32 v77, v0
	v_mov_b32_e32 v78, v0
	v_mov_b32_e32 v79, v0
	v_mov_b32_e32 v88, v0
	v_mov_b32_e32 v89, v0
	v_mov_b32_e32 v90, v0
	v_mov_b32_e32 v91, v0
	v_mov_b32_e32 v92, v0
	v_mov_b32_e32 v93, v0
	v_mov_b32_e32 v94, v0
	v_mov_b32_e32 v95, v0
	v_mov_b32_e32 v104, v0
	v_mov_b32_e32 v105, v0
	v_mov_b32_e32 v106, v0
	v_mov_b32_e32 v107, v0
	v_mov_b32_e32 v108, v0
	v_mov_b32_e32 v109, v0
	v_mov_b32_e32 v110, v0
	v_mov_b32_e32 v111, v0
	v_mov_b32_e32 v120, v0
	v_mov_b32_e32 v121, v0
	v_mov_b32_e32 v122, v0
	v_mov_b32_e32 v123, v0
	v_mov_b32_e32 v124, v0
	v_mov_b32_e32 v125, v0
	v_mov_b32_e32 v126, v0
	v_mov_b32_e32 v127, v0
	s_cmpk_gt_u32 s48, 0xff
	s_cbranch_scc0 .Lgin_leadp
	s_barrier
	s_branch .Lgin_enter

.Lgin_epi:
	s_setprio 0
	s_nop 0
	s_nop 0
	s_nop 0
	s_nop 0
	s_nop 0
	s_waitcnt vmcnt(0)
	v_fmamk_f32 v130, v156, 0x3a800000, v235
	v_mul_f32_e32 v131, 0x4b800000, v130
	v_cmp_gt_f32_e32 vcc, s86, v130
	s_cmp_lt_i32 s40, 4
	s_cselect_b64 s[14:15], -1, 0
	v_cndmask_b32_e32 v130, v130, v131, vcc
	v_rsq_f32_e32 v130, v130
	s_cmp_gt_i32 s40, 3
	v_mul_f32_e32 v131, 0x45800000, v130
	v_cndmask_b32_e32 v156, v130, v131, vcc
	v_pk_mul_f32 v[126:127], v[156:157], v[126:127] op_sel_hi:[0,1]
	v_pk_mul_f32 v[124:125], v[156:157], v[124:125] op_sel_hi:[0,1]
	v_pk_mul_f32 v[158:159], v[156:157], v[122:123] op_sel_hi:[0,1]
	v_pk_mul_f32 v[160:161], v[156:157], v[120:121] op_sel_hi:[0,1]
	s_cbranch_scc1 .LBB0_274
	v_mul_f32_e32 v121, 0x3d372713, v160
	v_mul_f32_e32 v121, v160, v121
	v_fma_f32 v121, v160, v121, v160
	v_mul_f32_e32 v121, 0x3fcc422a, v121
	v_mul_f32_e32 v121, 0xbfb8aa3b, v121
	v_exp_f32_e32 v121, v121
	v_mul_f32_e32 v120, 0x3d372713, v124
	v_mul_f32_e32 v120, v124, v120
	v_mov_b32_e32 v123, v125
	v_add_f32_e32 v121, 1.0, v121
	v_rcp_f32_e32 v122, v121
	v_mul_f32_e32 v121, 0x3d372713, v125
	v_mul_f32_e32 v121, v125, v121
	v_fma_f32 v120, v124, v120, v124
	v_fmac_f32_e32 v123, v123, v121
	v_mul_f32_e32 v120, 0x3fcc422a, v120
	v_mul_f32_e32 v121, 0x3fcc422a, v123
	v_mul_f32_e32 v120, 0xbfb8aa3b, v120
	v_mul_f32_e32 v121, 0xbfb8aa3b, v121
	v_mul_f32_e32 v131, 0x3d372713, v158
	v_exp_f32_e32 v120, v120
	v_exp_f32_e32 v121, v121
	v_mul_f32_e32 v131, v158, v131
	v_fma_f32 v131, v158, v131, v158
	v_mul_f32_e32 v131, 0x3fcc422a, v131
	v_mul_f32_e32 v131, 0xbfb8aa3b, v131
	v_add_f32_e32 v120, 1.0, v120
	v_add_f32_e32 v121, 1.0, v121
	v_exp_f32_e32 v131, v131
	v_rcp_f32_e32 v120, v120
	v_rcp_f32_e32 v121, v121
	v_mul_f32_e32 v123, 0x3d372713, v161
	v_mul_f32_e32 v123, v161, v123
	v_mov_b32_e32 v130, v161
	v_fmac_f32_e32 v130, v130, v123
	v_add_f32_e32 v131, 1.0, v131
	v_mul_f32_e32 v123, 0x3fcc422a, v130
	v_mul_f32_e32 v130, 0x3d372713, v126
	v_rcp_f32_e32 v132, v131
	v_mul_f32_e32 v131, 0x3d372713, v127
	v_pk_mul_f32 v[124:125], v[124:125], v[120:121]
	v_mul_f32_e32 v120, 0x3d372713, v159
	v_mul_f32_e32 v130, v126, v130
	v_mul_f32_e32 v131, v127, v131
	v_mul_f32_e32 v120, v159, v120
	v_fma_f32 v130, v126, v130, v126
	v_fma_f32 v131, v127, v131, v127
	v_fma_f32 v120, v159, v120, v159
	v_mul_f32_e32 v130, 0x3fcc422a, v130
	v_mul_f32_e32 v131, 0x3fcc422a, v131
	v_mul_f32_e32 v120, 0x3fcc422a, v120
	v_mul_f32_e32 v123, 0xbfb8aa3b, v123
	v_mul_f32_e32 v130, 0xbfb8aa3b, v130
	v_mul_f32_e32 v131, 0xbfb8aa3b, v131
	v_mul_f32_e32 v120, 0xbfb8aa3b, v120
	v_exp_f32_e32 v123, v123
	v_exp_f32_e32 v130, v130
	v_exp_f32_e32 v131, v131
	v_exp_f32_e32 v120, v120
	v_add_f32_e32 v123, 1.0, v123
	v_add_f32_e32 v130, 1.0, v130
	v_add_f32_e32 v131, 1.0, v131
	v_add_f32_e32 v120, 1.0, v120
	v_rcp_f32_e32 v123, v123
	v_rcp_f32_e32 v130, v130
	v_rcp_f32_e32 v131, v131
	v_rcp_f32_e32 v133, v120
	v_pk_mul_f32 v[160:161], v[160:161], v[122:123]
	v_pk_mul_f32 v[126:127], v[126:127], v[130:131]
	v_pk_mul_f32 v[158:159], v[158:159], v[132:133]

.LBB0_344:
	s_add_u32 s30, s18, 0xb0080
	s_addc_u32 s31, s19, 0
	s_add_u32 s0, s14, 0x100
	v_mov_b32_e32 v0, 0
	s_addc_u32 s1, s15, 0
	s_mov_b32 s25, -2
	v_mov_b32_e32 v1, v0
	v_mov_b32_e32 v2, v0
	v_mov_b32_e32 v3, v0
	v_mov_b32_e32 v4, v0
	v_mov_b32_e32 v5, v0
	v_mov_b32_e32 v6, v0
	v_mov_b32_e32 v7, v0
	v_mov_b32_e32 v16, v0
	v_mov_b32_e32 v17, v0
	v_mov_b32_e32 v18, v0
	v_mov_b32_e32 v19, v0
	v_mov_b32_e32 v20, v0
	v_mov_b32_e32 v21, v0
	v_mov_b32_e32 v22, v0
	v_mov_b32_e32 v23, v0
	v_mov_b32_e32 v32, v0
	v_mov_b32_e32 v33, v0
	v_mov_b32_e32 v34, v0
	v_mov_b32_e32 v35, v0
	v_mov_b32_e32 v36, v0
	v_mov_b32_e32 v37, v0
	v_mov_b32_e32 v38, v0
	v_mov_b32_e32 v39, v0
	v_mov_b32_e32 v48, v0
	v_mov_b32_e32 v49, v0
	v_mov_b32_e32 v50, v0
	v_mov_b32_e32 v51, v0
	v_mov_b32_e32 v52, v0
	v_mov_b32_e32 v53, v0
	v_mov_b32_e32 v54, v0
	v_mov_b32_e32 v55, v0
	v_mov_b32_e32 v8, v0
	v_mov_b32_e32 v9, v0
	v_mov_b32_e32 v10, v0
	v_mov_b32_e32 v11, v0
	v_mov_b32_e32 v12, v0
	v_mov_b32_e32 v13, v0
	v_mov_b32_e32 v14, v0
	v_mov_b32_e32 v15, v0
	v_mov_b32_e32 v24, v0
	v_mov_b32_e32 v25, v0
	v_mov_b32_e32 v26, v0
	v_mov_b32_e32 v27, v0
	v_mov_b32_e32 v28, v0
	v_mov_b32_e32 v29, v0
	v_mov_b32_e32 v30, v0
	v_mov_b32_e32 v31, v0
	v_mov_b32_e32 v40, v0
	v_mov_b32_e32 v41, v0
	v_mov_b32_e32 v42, v0
	v_mov_b32_e32 v43, v0
	v_mov_b32_e32 v44, v0
	v_mov_b32_e32 v45, v0
	v_mov_b32_e32 v46, v0
	v_mov_b32_e32 v47, v0
	v_mov_b32_e32 v56, v0
	v_mov_b32_e32 v57, v0
	v_mov_b32_e32 v58, v0
	v_mov_b32_e32 v59, v0
	v_mov_b32_e32 v60, v0
	v_mov_b32_e32 v61, v0
	v_mov_b32_e32 v62, v0
	v_mov_b32_e32 v63, v0
	v_mov_b32_e32 v64, v0
	v_mov_b32_e32 v65, v0
	v_mov_b32_e32 v66, v0
	v_mov_b32_e32 v67, v0
	v_mov_b32_e32 v68, v0
	v_mov_b32_e32 v69, v0
	v_mov_b32_e32 v70, v0
	v_mov_b32_e32 v71, v0
	v_mov_b32_e32 v80, v0
	v_mov_b32_e32 v81, v0
	v_mov_b32_e32 v82, v0
	v_mov_b32_e32 v83, v0
	v_mov_b32_e32 v84, v0
	v_mov_b32_e32 v85, v0
	v_mov_b32_e32 v86, v0
	v_mov_b32_e32 v87, v0
	v_mov_b32_e32 v96, v0
	v_mov_b32_e32 v97, v0
	v_mov_b32_e32 v98, v0
	v_mov_b32_e32 v99, v0
	v_mov_b32_e32 v100, v0
	v_mov_b32_e32 v101, v0
	v_mov_b32_e32 v102, v0
	v_mov_b32_e32 v103, v0
	v_mov_b32_e32 v112, v0
	v_mov_b32_e32 v113, v0
	v_mov_b32_e32 v114, v0
	v_mov_b32_e32 v115, v0
	v_mov_b32_e32 v116, v0
	v_mov_b32_e32 v117, v0
	v_mov_b32_e32 v118, v0
	v_mov_b32_e32 v119, v0
	v_mov_b32_e32 v72, v0
	v_mov_b32_e32 v73, v0
	v_mov_b32_e32 v74, v0
	v_mov_b32_e32 v75, v0
	v_mov_b32_e32 v76, v0
	v_mov_b32_e32 v77, v0
	v_mov_b32_e32 v78, v0
	v_mov_b32_e32 v79, v0
	v_mov_b32_e32 v88, v0
	v_mov_b32_e32 v89, v0
	v_mov_b32_e32 v90, v0
	v_mov_b32_e32 v91, v0
	v_mov_b32_e32 v92, v0
	v_mov_b32_e32 v93, v0
	v_mov_b32_e32 v94, v0
	v_mov_b32_e32 v95, v0
	v_mov_b32_e32 v104, v0
	v_mov_b32_e32 v105, v0
	v_mov_b32_e32 v106, v0
	v_mov_b32_e32 v107, v0
	v_mov_b32_e32 v108, v0
	v_mov_b32_e32 v109, v0
	v_mov_b32_e32 v110, v0
	v_mov_b32_e32 v111, v0
	v_mov_b32_e32 v120, v0
	v_mov_b32_e32 v121, v0
	v_mov_b32_e32 v122, v0
	v_mov_b32_e32 v123, v0
	v_mov_b32_e32 v124, v0
	v_mov_b32_e32 v125, v0
	v_mov_b32_e32 v126, v0
	v_mov_b32_e32 v127, v0
	s_cmpk_gt_u32 s48, 0xff
	s_cbranch_scc0 .Lg2_leadp
	s_barrier
	s_branch .Lg2_enter

.Lg2_epi:
	s_setprio 0
	s_nop 0
	s_nop 0
	s_nop 0
	s_nop 0
	s_nop 0
	s_cmp_lt_i32 s47, 0
	s_cselect_b64 s[14:15], -1, 0
	s_cmp_gt_i32 s47, -1
	s_cbranch_scc1 .LBB0_348
	v_mul_f32_e32 v131, 0x3d372713, v120
	v_mul_f32_e32 v131, v120, v131
	v_fma_f32 v131, v120, v131, v120
	v_mul_f32_e32 v131, 0x3fcc422a, v131
	v_mul_f32_e32 v131, 0xbfb8aa3b, v131
	v_exp_f32_e32 v131, v131
	v_mul_f32_e32 v130, 0x3d372713, v124
	v_mul_f32_e32 v130, v124, v130
	v_fma_f32 v130, v124, v130, v124
	v_add_f32_e32 v131, 1.0, v131
	v_rcp_f32_e32 v132, v131
	v_mul_f32_e32 v131, 0x3d372713, v125
	v_mul_f32_e32 v131, v125, v131
	v_fma_f32 v131, v125, v131, v125
	v_mul_f32_e32 v130, 0x3fcc422a, v130
	v_mul_f32_e32 v131, 0x3fcc422a, v131
	v_mul_f32_e32 v130, 0xbfb8aa3b, v130
	v_mul_f32_e32 v131, 0xbfb8aa3b, v131
	v_mul_f32_e32 v135, 0x3d372713, v122
	v_exp_f32_e32 v130, v130
	v_exp_f32_e32 v131, v131
	v_mul_f32_e32 v135, v122, v135
	v_fma_f32 v135, v122, v135, v122
	v_mul_f32_e32 v135, 0x3fcc422a, v135
	v_mul_f32_e32 v135, 0xbfb8aa3b, v135
	v_add_f32_e32 v130, 1.0, v130
	v_add_f32_e32 v131, 1.0, v131
	v_exp_f32_e32 v135, v135
	v_rcp_f32_e32 v130, v130
	v_rcp_f32_e32 v131, v131
	v_mul_f32_e32 v133, 0x3d372713, v121
	v_add_f32_e32 v135, 1.0, v135
	v_mul_f32_e32 v134, 0x3d372713, v126
	v_rcp_f32_e32 v136, v135
	v_mul_f32_e32 v135, 0x3d372713, v127
	v_pk_mul_f32 v[124:125], v[124:125], v[130:131]
	v_mul_f32_e32 v130, 0x3d372713, v123
	v_mul_f32_e32 v133, v121, v133
	v_mul_f32_e32 v134, v126, v134
	v_mul_f32_e32 v135, v127, v135
	v_mul_f32_e32 v130, v123, v130
	v_fma_f32 v133, v121, v133, v121
	v_fma_f32 v134, v126, v134, v126
	v_fma_f32 v135, v127, v135, v127
	v_fma_f32 v130, v123, v130, v123
	v_mul_f32_e32 v133, 0x3fcc422a, v133
	v_mul_f32_e32 v134, 0x3fcc422a, v134
	v_mul_f32_e32 v135, 0x3fcc422a, v135
	v_mul_f32_e32 v130, 0x3fcc422a, v130
	v_mul_f32_e32 v133, 0xbfb8aa3b, v133
	v_mul_f32_e32 v134, 0xbfb8aa3b, v134
	v_mul_f32_e32 v135, 0xbfb8aa3b, v135
	v_mul_f32_e32 v130, 0xbfb8aa3b, v130
	v_exp_f32_e32 v133, v133
	v_exp_f32_e32 v134, v134
	v_exp_f32_e32 v135, v135
	v_exp_f32_e32 v130, v130
	v_add_f32_e32 v133, 1.0, v133
	v_add_f32_e32 v134, 1.0, v134
	v_add_f32_e32 v135, 1.0, v135
	v_add_f32_e32 v130, 1.0, v130
	v_rcp_f32_e32 v133, v133
	v_rcp_f32_e32 v134, v134
	v_rcp_f32_e32 v135, v135
	v_rcp_f32_e32 v137, v130
	v_pk_mul_f32 v[120:121], v[120:121], v[132:133]
	v_pk_mul_f32 v[126:127], v[126:127], v[134:135]
	v_pk_mul_f32 v[122:123], v[122:123], v[136:137]

.LBB0_390:
	v_mov_b64_e32 v[0:1], 0x1080
	s_ashr_i32 s13, s12, 31
	v_cmp_lt_i64_e32 vcc, s[30:31], v[0:1]
	s_lshl_b64 s[24:25], s[12:13], 19
	v_readlane_b32 s30, v252, 55
	v_readlane_b32 s31, v252, 56
	s_add_u32 s40, s30, s24
	s_addc_u32 s41, s31, s25
	v_lshl_add_u32 v154, s20, 8, v143
	v_readlane_b32 s30, v252, 43
	v_ashrrev_i32_e32 v155, 31, v154
	v_readlane_b32 s31, v252, 44
	s_and_b64 s[24:25], vcc, exec
	s_cselect_b32 s1, s41, s19
	v_lshl_add_u64 v[0:1], v[154:155], 2, s[30:31]
	global_load_dword v165, v[0:1], off
	global_load_dword v164, v[0:1], off offset:64
	global_load_dword v163, v[0:1], off offset:128
	global_load_dword v162, v[0:1], off offset:192
	global_load_dword v161, v[0:1], off offset:512
	global_load_dword v160, v[0:1], off offset:576
	global_load_dword v159, v[0:1], off offset:640
	global_load_dword v155, v[0:1], off offset:704
	s_cselect_b32 s13, s40, s18
	s_ashr_i32 s9, s8, 31
	s_lshl_b64 s[24:25], s[8:9], 19
	s_add_u32 s42, s16, s24
	s_addc_u32 s43, s17, s25
	s_and_b64 s[24:25], vcc, exec
	s_cselect_b32 s9, s43, s15
	s_cselect_b32 s24, s42, s14
	s_add_u32 s30, s18, 0x40080
	s_addc_u32 s31, s19, 0
	s_add_u32 s25, s14, 0x100
	v_mov_b32_e32 v8, 0
	s_addc_u32 s47, s15, 0
	s_mov_b32 s92, -2
	v_mov_b32_e32 v9, v8
	v_mov_b32_e32 v10, v8
	v_mov_b32_e32 v11, v8
	v_mov_b32_e32 v12, v8
	v_mov_b32_e32 v13, v8
	v_mov_b32_e32 v14, v8
	v_mov_b32_e32 v15, v8
	v_mov_b32_e32 v24, v8
	v_mov_b32_e32 v25, v8
	v_mov_b32_e32 v26, v8
	v_mov_b32_e32 v27, v8
	v_mov_b32_e32 v28, v8
	v_mov_b32_e32 v29, v8
	v_mov_b32_e32 v30, v8
	v_mov_b32_e32 v31, v8
	v_mov_b32_e32 v40, v8
	v_mov_b32_e32 v41, v8
	v_mov_b32_e32 v42, v8
	v_mov_b32_e32 v43, v8
	v_mov_b32_e32 v44, v8
	v_mov_b32_e32 v45, v8
	v_mov_b32_e32 v46, v8
	v_mov_b32_e32 v47, v8
	v_mov_b32_e32 v56, v8
	v_mov_b32_e32 v57, v8
	v_mov_b32_e32 v58, v8
	v_mov_b32_e32 v59, v8
	v_mov_b32_e32 v60, v8
	v_mov_b32_e32 v61, v8
	v_mov_b32_e32 v62, v8
	v_mov_b32_e32 v63, v8
	v_mov_b32_e32 v0, v8
	v_mov_b32_e32 v1, v8
	v_mov_b32_e32 v2, v8
	v_mov_b32_e32 v3, v8
	v_mov_b32_e32 v4, v8
	v_mov_b32_e32 v5, v8
	v_mov_b32_e32 v6, v8
	v_mov_b32_e32 v7, v8
	v_mov_b32_e32 v16, v8
	v_mov_b32_e32 v17, v8
	v_mov_b32_e32 v18, v8
	v_mov_b32_e32 v19, v8
	v_mov_b32_e32 v20, v8
	v_mov_b32_e32 v21, v8
	v_mov_b32_e32 v22, v8
	v_mov_b32_e32 v23, v8
	v_mov_b32_e32 v32, v8
	v_mov_b32_e32 v33, v8
	v_mov_b32_e32 v34, v8
	v_mov_b32_e32 v35, v8
	v_mov_b32_e32 v36, v8
	v_mov_b32_e32 v37, v8
	v_mov_b32_e32 v38, v8
	v_mov_b32_e32 v39, v8
	v_mov_b32_e32 v48, v8
	v_mov_b32_e32 v49, v8
	v_mov_b32_e32 v50, v8
	v_mov_b32_e32 v51, v8
	v_mov_b32_e32 v52, v8
	v_mov_b32_e32 v53, v8
	v_mov_b32_e32 v54, v8
	v_mov_b32_e32 v55, v8
	v_mov_b32_e32 v72, v8
	v_mov_b32_e32 v73, v8
	v_mov_b32_e32 v74, v8
	v_mov_b32_e32 v75, v8
	v_mov_b32_e32 v76, v8
	v_mov_b32_e32 v77, v8
	v_mov_b32_e32 v78, v8
	v_mov_b32_e32 v79, v8
	v_mov_b32_e32 v88, v8
	v_mov_b32_e32 v89, v8
	v_mov_b32_e32 v90, v8
	v_mov_b32_e32 v91, v8
	v_mov_b32_e32 v92, v8
	v_mov_b32_e32 v93, v8
	v_mov_b32_e32 v94, v8
	v_mov_b32_e32 v95, v8
	v_mov_b32_e32 v104, v8
	v_mov_b32_e32 v105, v8
	v_mov_b32_e32 v106, v8
	v_mov_b32_e32 v107, v8
	v_mov_b32_e32 v108, v8
	v_mov_b32_e32 v109, v8
	v_mov_b32_e32 v110, v8
	v_mov_b32_e32 v111, v8
	v_mov_b32_e32 v120, v8
	v_mov_b32_e32 v121, v8
	v_mov_b32_e32 v122, v8
	v_mov_b32_e32 v123, v8
	v_mov_b32_e32 v124, v8
	v_mov_b32_e32 v125, v8
	v_mov_b32_e32 v126, v8
	v_mov_b32_e32 v127, v8
	v_mov_b32_e32 v64, v8
	v_mov_b32_e32 v65, v8
	v_mov_b32_e32 v66, v8
	v_mov_b32_e32 v67, v8
	v_mov_b32_e32 v68, v8
	v_mov_b32_e32 v69, v8
	v_mov_b32_e32 v70, v8
	v_mov_b32_e32 v71, v8
	v_mov_b32_e32 v80, v8
	v_mov_b32_e32 v81, v8
	v_mov_b32_e32 v82, v8
	v_mov_b32_e32 v83, v8
	v_mov_b32_e32 v84, v8
	v_mov_b32_e32 v85, v8
	v_mov_b32_e32 v86, v8
	v_mov_b32_e32 v87, v8
	v_mov_b32_e32 v96, v8
	v_mov_b32_e32 v97, v8
	v_mov_b32_e32 v98, v8
	v_mov_b32_e32 v99, v8
	v_mov_b32_e32 v100, v8
	v_mov_b32_e32 v101, v8
	v_mov_b32_e32 v102, v8
	v_mov_b32_e32 v103, v8
	v_mov_b32_e32 v112, v8
	v_mov_b32_e32 v113, v8
	v_mov_b32_e32 v114, v8
	v_mov_b32_e32 v115, v8
	v_mov_b32_e32 v116, v8
	v_mov_b32_e32 v117, v8
	v_mov_b32_e32 v118, v8
	v_mov_b32_e32 v119, v8
	s_cmpk_gt_u32 s4, 0xff
	s_cbranch_scc0 .Lg1_leadp
	s_barrier
	s_branch .Lg1_enter

.Lg1_epi:
	s_setprio 0
	s_nop 0
	s_nop 0
	s_nop 0
	s_nop 0
	s_nop 0
	s_waitcnt vmcnt(0)
	v_fmamk_f32 v132, v165, 0x3a800000, v235
	v_cmp_gt_f32_e32 vcc, s86, v132
	v_mul_f32_e32 v133, 0x4b800000, v132
	v_pk_mul_f32 v[126:127], v[118:119], v[126:127]
	v_cndmask_b32_e32 v132, v132, v133, vcc
	v_rsq_f32_e32 v132, v132
	v_pk_mul_f32 v[122:123], v[114:115], v[122:123]
	v_lshl_or_b32 v130, s0, 7, v157
	v_ashrrev_i32_e32 v131, 31, v130
	v_mul_f32_e32 v133, 0x45800000, v132
	v_cndmask_b32_e32 v132, v132, v133, vcc
	v_mul_f32_e32 v133, 0xbfb8aa3b, v132
	v_mul_f32_e32 v135, v133, v112
	v_exp_f32_e32 v135, v135
	v_mul_f32_e32 v134, v133, v116
	v_exp_f32_e32 v134, v134
	v_mul_f32_e32 v132, v132, v132
	v_add_f32_e32 v135, 1.0, v135
	v_rcp_f32_e32 v136, v135
	v_mul_f32_e32 v135, v133, v117
	v_exp_f32_e32 v135, v135
	v_add_f32_e32 v134, 1.0, v134
	v_rcp_f32_e32 v134, v134
	v_pk_mul_f32 v[116:117], v[116:117], v[124:125]
	v_add_f32_e32 v135, 1.0, v135
	v_rcp_f32_e32 v135, v135
	v_mul_f32_e32 v118, v133, v118
	v_mul_f32_e32 v119, v133, v119
	v_exp_f32_e32 v118, v118
	v_pk_mul_f32 v[124:125], v[132:133], v[134:135] op_sel_hi:[0,1]
	v_pk_mul_f32 v[116:117], v[124:125], v[116:117]
	v_mul_f32_e32 v124, v133, v113
	v_exp_f32_e32 v124, v124
	v_mul_f32_e32 v114, v133, v114
	v_exp_f32_e32 v119, v119
	v_mul_f32_e32 v115, v133, v115
	v_exp_f32_e32 v114, v114
	v_exp_f32_e32 v115, v115
	v_add_f32_e32 v124, 1.0, v124
	v_add_f32_e32 v118, 1.0, v118
	v_add_f32_e32 v119, 1.0, v119
	v_rcp_f32_e32 v137, v124
	v_rcp_f32_e32 v118, v118
	v_add_f32_e32 v114, 1.0, v114
	v_rcp_f32_e32 v119, v119
	v_add_f32_e32 v115, 1.0, v115
	v_rcp_f32_e32 v114, v114
	v_rcp_f32_e32 v115, v115
	v_pk_mul_f32 v[112:113], v[112:113], v[120:121]
	v_pk_mul_f32 v[120:121], v[132:133], v[136:137] op_sel_hi:[0,1]
	v_pk_mul_f32 v[118:119], v[132:133], v[118:119] op_sel_hi:[0,1]
	v_pk_mul_f32 v[112:113], v[120:121], v[112:113]
	v_pk_mul_f32 v[118:119], v[118:119], v[126:127]
	v_pk_mul_f32 v[114:115], v[132:133], v[114:115] op_sel_hi:[0,1]
	v_pk_mul_f32 v[114:115], v[114:115], v[122:123]
	v_cvt_pk_bf16_f32 v116, v116, v117
	v_cvt_pk_bf16_f32 v117, v118, v119
	v_cvt_pk_bf16_f32 v118, v112, v113
	v_mov_b64_e32 v[112:113], s[94:95]
	s_movk_i32 s9, 0x1600
	v_cvt_pk_bf16_f32 v119, v114, v115
	v_mad_i64_i32 v[120:121], s[0:1], v154, s9, v[112:113]
	v_lshlrev_b64 v[114:115], 1, v[130:131]
	v_lshl_add_u64 v[120:121], v[120:121], 0, v[114:115]
	global_store_dwordx4 v[120:121], v[116:119], off nt
	v_pk_mul_f32 v[106:107], v[98:99], v[106:107]
	v_pk_mul_f32 v[110:111], v[102:103], v[110:111]
	v_fmamk_f32 v116, v164, 0x3a800000, v235
	v_cmp_gt_f32_e32 vcc, s86, v116
	v_mul_f32_e32 v117, 0x4b800000, v116
	v_pk_mul_f32 v[90:91], v[82:83], v[90:91]
	v_cndmask_b32_e32 v116, v116, v117, vcc
	v_rsq_f32_e32 v116, v116
	v_pk_mul_f32 v[94:95], v[86:87], v[94:95]
	v_pk_mul_f32 v[74:75], v[66:67], v[74:75]
	v_pk_mul_f32 v[78:79], v[70:71], v[78:79]
	v_mul_f32_e32 v117, 0x45800000, v116
	v_cndmask_b32_e32 v116, v116, v117, vcc
	v_mul_f32_e32 v117, 0xbfb8aa3b, v116
	v_mul_f32_e32 v119, v117, v96
	v_exp_f32_e32 v119, v119
	v_mul_f32_e32 v118, v117, v100
	v_exp_f32_e32 v118, v118
	v_mul_f32_e32 v116, v116, v116
	v_add_f32_e32 v119, 1.0, v119
	v_rcp_f32_e32 v120, v119
	v_mul_f32_e32 v119, v117, v101
	v_exp_f32_e32 v119, v119
	v_add_f32_e32 v118, 1.0, v118
	v_rcp_f32_e32 v118, v118
	v_pk_mul_f32 v[100:101], v[100:101], v[108:109]
	v_add_f32_e32 v119, 1.0, v119
	v_rcp_f32_e32 v119, v119
	v_pk_mul_f32 v[58:59], v[50:51], v[58:59]
	v_pk_mul_f32 v[62:63], v[54:55], v[62:63]
	v_pk_mul_f32 v[42:43], v[34:35], v[42:43]
	v_pk_mul_f32 v[108:109], v[116:117], v[118:119] op_sel_hi:[0,1]
	v_pk_mul_f32 v[100:101], v[108:109], v[100:101]
	v_mul_f32_e32 v108, v117, v97
	v_exp_f32_e32 v108, v108
	v_pk_mul_f32 v[96:97], v[96:97], v[104:105]
	v_pk_mul_f32 v[46:47], v[38:39], v[46:47]
	v_pk_mul_f32 v[26:27], v[18:19], v[26:27]
	v_add_f32_e32 v108, 1.0, v108
	v_rcp_f32_e32 v121, v108
	v_or_b32_e32 v108, 16, v154
	v_pk_mul_f32 v[30:31], v[22:23], v[30:31]
	v_pk_mul_f32 v[10:11], v[2:3], v[10:11]
	v_pk_mul_f32 v[104:105], v[116:117], v[120:121] op_sel_hi:[0,1]
	v_pk_mul_f32 v[104:105], v[104:105], v[96:97]
	v_mul_f32_e32 v97, v117, v98
	v_exp_f32_e32 v97, v97
	v_mul_f32_e32 v96, v117, v102
	v_exp_f32_e32 v96, v96
	v_pk_mul_f32 v[14:15], v[6:7], v[14:15]
	v_add_f32_e32 v97, 1.0, v97
	v_rcp_f32_e32 v98, v97
	v_mul_f32_e32 v97, v117, v103
	v_exp_f32_e32 v97, v97
	v_add_f32_e32 v96, 1.0, v96
	v_rcp_f32_e32 v96, v96
	s_mov_b32 s20, s12
	v_add_f32_e32 v97, 1.0, v97
	v_rcp_f32_e32 v97, v97
	s_mov_b64 s[14:15], s[42:43]
	s_mov_b64 s[18:19], s[40:41]
	v_pk_mul_f32 v[96:97], v[116:117], v[96:97] op_sel_hi:[0,1]
	v_pk_mul_f32 v[102:103], v[96:97], v[110:111]
	v_mul_f32_e32 v96, v117, v99
	v_exp_f32_e32 v96, v96
	s_nop 0
	v_add_f32_e32 v96, 1.0, v96
	v_rcp_f32_e32 v99, v96
	s_nop 0
	v_pk_mul_f32 v[96:97], v[116:117], v[98:99] op_sel_hi:[0,1]
	v_pk_mul_f32 v[106:107], v[96:97], v[106:107]
	v_cvt_pk_bf16_f32 v96, v100, v101
	v_mad_i64_i32 v[100:101], s[0:1], v108, s9, v[112:113]
	v_cvt_pk_bf16_f32 v97, v102, v103
	v_cvt_pk_bf16_f32 v98, v104, v105
	v_cvt_pk_bf16_f32 v99, v106, v107
	v_lshl_add_u64 v[100:101], v[100:101], 0, v[114:115]
	global_store_dwordx4 v[100:101], v[96:99], off nt
	s_nop 1
	v_fmamk_f32 v96, v163, 0x3a800000, v235
	v_cmp_gt_f32_e32 vcc, s86, v96
	v_mul_f32_e32 v97, 0x4b800000, v96
	s_nop 0
	v_cndmask_b32_e32 v96, v96, v97, vcc
	v_rsq_f32_e32 v96, v96
	s_nop 0
	v_mul_f32_e32 v97, 0x45800000, v96
	v_cndmask_b32_e32 v96, v96, v97, vcc
	v_mul_f32_e32 v97, 0xbfb8aa3b, v96
	v_mul_f32_e32 v99, v97, v80
	v_exp_f32_e32 v99, v99
	v_mul_f32_e32 v98, v97, v84
	v_exp_f32_e32 v98, v98
	v_mul_f32_e32 v96, v96, v96
	v_add_f32_e32 v99, 1.0, v99
	v_rcp_f32_e32 v100, v99
	v_mul_f32_e32 v99, v97, v85
	v_exp_f32_e32 v99, v99
	v_add_f32_e32 v98, 1.0, v98
	v_rcp_f32_e32 v98, v98
	v_pk_mul_f32 v[84:85], v[84:85], v[92:93]
	v_add_f32_e32 v99, 1.0, v99
	v_rcp_f32_e32 v99, v99
	s_nop 0
	v_pk_mul_f32 v[92:93], v[96:97], v[98:99] op_sel_hi:[0,1]
	v_pk_mul_f32 v[84:85], v[92:93], v[84:85]
	v_mul_f32_e32 v92, v97, v81
	v_exp_f32_e32 v92, v92
	v_pk_mul_f32 v[80:81], v[80:81], v[88:89]
	v_add_f32_e32 v92, 1.0, v92
	v_rcp_f32_e32 v101, v92
	v_or_b32_e32 v92, 32, v154
	v_pk_mul_f32 v[88:89], v[96:97], v[100:101] op_sel_hi:[0,1]
	v_pk_mul_f32 v[88:89], v[88:89], v[80:81]
	v_mul_f32_e32 v81, v97, v82
	v_exp_f32_e32 v81, v81
	v_mul_f32_e32 v80, v97, v86
	v_exp_f32_e32 v80, v80
	v_add_f32_e32 v81, 1.0, v81
	v_rcp_f32_e32 v82, v81
	v_mul_f32_e32 v81, v97, v87
	v_exp_f32_e32 v81, v81
	v_add_f32_e32 v80, 1.0, v80
	v_rcp_f32_e32 v80, v80
	v_add_f32_e32 v81, 1.0, v81
	v_rcp_f32_e32 v81, v81
	s_nop 0
	v_pk_mul_f32 v[80:81], v[96:97], v[80:81] op_sel_hi:[0,1]
	v_pk_mul_f32 v[86:87], v[80:81], v[94:95]
	v_mul_f32_e32 v80, v97, v83
	v_exp_f32_e32 v80, v80
	s_nop 0
	v_add_f32_e32 v80, 1.0, v80
	v_rcp_f32_e32 v83, v80
	s_nop 0
	v_pk_mul_f32 v[80:81], v[96:97], v[82:83] op_sel_hi:[0,1]
	v_pk_mul_f32 v[90:91], v[80:81], v[90:91]
	v_cvt_pk_bf16_f32 v80, v84, v85
	v_mad_i64_i32 v[84:85], s[0:1], v92, s9, v[112:113]
	v_cvt_pk_bf16_f32 v81, v86, v87
	v_cvt_pk_bf16_f32 v82, v88, v89
	v_cvt_pk_bf16_f32 v83, v90, v91
	v_lshl_add_u64 v[84:85], v[84:85], 0, v[114:115]
	global_store_dwordx4 v[84:85], v[80:83], off nt
	s_nop 1
	v_fmamk_f32 v80, v162, 0x3a800000, v235
	v_cmp_gt_f32_e32 vcc, s86, v80
	v_mul_f32_e32 v81, 0x4b800000, v80
	s_nop 0
	v_cndmask_b32_e32 v80, v80, v81, vcc
	v_rsq_f32_e32 v80, v80
	s_nop 0
	v_mul_f32_e32 v81, 0x45800000, v80
	v_cndmask_b32_e32 v80, v80, v81, vcc
	v_mul_f32_e32 v81, 0xbfb8aa3b, v80
	v_mul_f32_e32 v83, v81, v64
	v_exp_f32_e32 v83, v83
	v_mul_f32_e32 v82, v81, v68
	v_exp_f32_e32 v82, v82
	v_mul_f32_e32 v80, v80, v80
	v_add_f32_e32 v83, 1.0, v83
	v_rcp_f32_e32 v84, v83
	v_mul_f32_e32 v83, v81, v69
	v_exp_f32_e32 v83, v83
	v_add_f32_e32 v82, 1.0, v82
	v_rcp_f32_e32 v82, v82
	v_pk_mul_f32 v[68:69], v[68:69], v[76:77]
	v_add_f32_e32 v83, 1.0, v83
	v_rcp_f32_e32 v83, v83
	s_nop 0
	v_pk_mul_f32 v[76:77], v[80:81], v[82:83] op_sel_hi:[0,1]
	v_pk_mul_f32 v[68:69], v[76:77], v[68:69]
	v_mul_f32_e32 v76, v81, v65
	v_exp_f32_e32 v76, v76
	v_pk_mul_f32 v[64:65], v[64:65], v[72:73]
	v_add_f32_e32 v76, 1.0, v76
	v_rcp_f32_e32 v85, v76
	v_or_b32_e32 v76, 48, v154
	v_pk_mul_f32 v[72:73], v[80:81], v[84:85] op_sel_hi:[0,1]
	v_pk_mul_f32 v[72:73], v[72:73], v[64:65]
	v_mul_f32_e32 v65, v81, v66
	v_exp_f32_e32 v65, v65
	v_mul_f32_e32 v64, v81, v70
	v_exp_f32_e32 v64, v64
	v_add_f32_e32 v65, 1.0, v65
	v_rcp_f32_e32 v66, v65
	v_mul_f32_e32 v65, v81, v71
	v_exp_f32_e32 v65, v65
	v_add_f32_e32 v64, 1.0, v64
	v_rcp_f32_e32 v64, v64
	v_add_f32_e32 v65, 1.0, v65
	v_rcp_f32_e32 v65, v65
	s_nop 0
	v_pk_mul_f32 v[64:65], v[80:81], v[64:65] op_sel_hi:[0,1]
	v_pk_mul_f32 v[70:71], v[64:65], v[78:79]
	v_mul_f32_e32 v64, v81, v67
	v_exp_f32_e32 v64, v64
	s_nop 0
	v_add_f32_e32 v64, 1.0, v64
	v_rcp_f32_e32 v67, v64
	s_nop 0
	v_pk_mul_f32 v[64:65], v[80:81], v[66:67] op_sel_hi:[0,1]
	v_pk_mul_f32 v[74:75], v[64:65], v[74:75]
	v_cvt_pk_bf16_f32 v64, v68, v69
	v_mad_i64_i32 v[68:69], s[0:1], v76, s9, v[112:113]
	v_cvt_pk_bf16_f32 v65, v70, v71
	v_cvt_pk_bf16_f32 v66, v72, v73
	v_cvt_pk_bf16_f32 v67, v74, v75
	v_lshl_add_u64 v[68:69], v[68:69], 0, v[114:115]
	global_store_dwordx4 v[68:69], v[64:67], off nt
	s_nop 1
	v_fmamk_f32 v64, v161, 0x3a800000, v235
	v_cmp_gt_f32_e32 vcc, s86, v64
	v_mul_f32_e32 v66, 0x4b800000, v64
	v_add_u32_e32 v65, 0x80, v154
	v_cndmask_b32_e32 v64, v64, v66, vcc
	v_rsq_f32_e32 v64, v64
	s_nop 0
	v_mul_f32_e32 v66, 0x45800000, v64
	v_cndmask_b32_e32 v64, v64, v66, vcc
	v_mul_f32_e32 v70, 0xbfb8aa3b, v64
	v_mul_f32_e32 v67, v70, v48
	v_exp_f32_e32 v67, v67
	v_mul_f32_e32 v66, v70, v52
	v_exp_f32_e32 v66, v66
	v_mul_f32_e32 v64, v64, v64
	v_add_f32_e32 v67, 1.0, v67
	v_rcp_f32_e32 v68, v67
	v_mul_f32_e32 v67, v70, v53
	v_exp_f32_e32 v67, v67
	v_add_f32_e32 v66, 1.0, v66
	v_rcp_f32_e32 v66, v66
	v_pk_mul_f32 v[52:53], v[52:53], v[60:61]
	v_add_f32_e32 v67, 1.0, v67
	v_rcp_f32_e32 v67, v67
	s_nop 0
	v_pk_mul_f32 v[60:61], v[64:65], v[66:67] op_sel_hi:[0,1]
	v_pk_mul_f32 v[52:53], v[60:61], v[52:53]
	v_mul_f32_e32 v60, v70, v49
	v_exp_f32_e32 v60, v60
	v_pk_mul_f32 v[48:49], v[48:49], v[56:57]
	v_add_f32_e32 v60, 1.0, v60
	v_rcp_f32_e32 v69, v60
	s_nop 0
	v_pk_mul_f32 v[56:57], v[64:65], v[68:69] op_sel_hi:[0,1]
	v_pk_mul_f32 v[56:57], v[56:57], v[48:49]
	v_mul_f32_e32 v49, v70, v50
	v_exp_f32_e32 v49, v49
	v_mul_f32_e32 v48, v70, v54
	v_exp_f32_e32 v48, v48
	v_add_f32_e32 v49, 1.0, v49
	v_rcp_f32_e32 v50, v49
	v_mul_f32_e32 v49, v70, v55
	v_exp_f32_e32 v49, v49
	v_add_f32_e32 v48, 1.0, v48
	v_rcp_f32_e32 v48, v48
	v_add_f32_e32 v49, 1.0, v49
	v_rcp_f32_e32 v49, v49
	s_nop 0
	v_pk_mul_f32 v[48:49], v[64:65], v[48:49] op_sel_hi:[0,1]
	v_pk_mul_f32 v[54:55], v[48:49], v[62:63]
	v_mul_f32_e32 v48, v70, v51
	v_exp_f32_e32 v48, v48
	s_nop 0
	v_add_f32_e32 v48, 1.0, v48
	v_rcp_f32_e32 v51, v48
	s_nop 0
	v_pk_mul_f32 v[48:49], v[64:65], v[50:51] op_sel_hi:[0,1]
	v_pk_mul_f32 v[58:59], v[48:49], v[58:59]
	v_cvt_pk_bf16_f32 v48, v52, v53
	v_mad_i64_i32 v[52:53], s[0:1], v65, s9, v[112:113]
	v_cvt_pk_bf16_f32 v49, v54, v55
	v_cvt_pk_bf16_f32 v50, v56, v57
	v_cvt_pk_bf16_f32 v51, v58, v59
	v_lshl_add_u64 v[52:53], v[52:53], 0, v[114:115]
	global_store_dwordx4 v[52:53], v[48:51], off nt
	s_nop 1
	v_fmamk_f32 v48, v160, 0x3a800000, v235
	v_cmp_gt_f32_e32 vcc, s86, v48
	v_mul_f32_e32 v49, 0x4b800000, v48
	s_nop 0
	v_cndmask_b32_e32 v48, v48, v49, vcc
	v_rsq_f32_e32 v48, v48
	s_nop 0
	v_mul_f32_e32 v49, 0x45800000, v48
	v_cndmask_b32_e32 v48, v48, v49, vcc
	v_mul_f32_e32 v49, 0xbfb8aa3b, v48
	v_mul_f32_e32 v51, v49, v32
	v_exp_f32_e32 v51, v51
	v_mul_f32_e32 v50, v49, v36
	v_exp_f32_e32 v50, v50
	v_mul_f32_e32 v48, v48, v48
	v_add_f32_e32 v51, 1.0, v51
	v_rcp_f32_e32 v52, v51
	v_mul_f32_e32 v51, v49, v37
	v_exp_f32_e32 v51, v51
	v_add_f32_e32 v50, 1.0, v50
	v_rcp_f32_e32 v50, v50
	v_pk_mul_f32 v[36:37], v[36:37], v[44:45]
	v_add_f32_e32 v51, 1.0, v51
	v_rcp_f32_e32 v51, v51
	s_nop 0
	v_pk_mul_f32 v[44:45], v[48:49], v[50:51] op_sel_hi:[0,1]
	v_pk_mul_f32 v[36:37], v[44:45], v[36:37]
	v_mul_f32_e32 v44, v49, v33
	v_exp_f32_e32 v44, v44
	v_pk_mul_f32 v[32:33], v[32:33], v[40:41]
	v_add_f32_e32 v44, 1.0, v44
	v_rcp_f32_e32 v53, v44
	v_add_u32_e32 v44, 0x90, v154
	v_pk_mul_f32 v[40:41], v[48:49], v[52:53] op_sel_hi:[0,1]
	v_pk_mul_f32 v[40:41], v[40:41], v[32:33]
	v_mul_f32_e32 v33, v49, v34
	v_exp_f32_e32 v33, v33
	v_mul_f32_e32 v32, v49, v38
	v_exp_f32_e32 v32, v32
	v_add_f32_e32 v33, 1.0, v33
	v_rcp_f32_e32 v34, v33
	v_mul_f32_e32 v33, v49, v39
	v_exp_f32_e32 v33, v33
	v_add_f32_e32 v32, 1.0, v32
	v_rcp_f32_e32 v32, v32
	v_add_f32_e32 v33, 1.0, v33
	v_rcp_f32_e32 v33, v33
	s_nop 0
	v_pk_mul_f32 v[32:33], v[48:49], v[32:33] op_sel_hi:[0,1]
	v_pk_mul_f32 v[38:39], v[32:33], v[46:47]
	v_mul_f32_e32 v32, v49, v35
	v_exp_f32_e32 v32, v32
	s_nop 0
	v_add_f32_e32 v32, 1.0, v32
	v_rcp_f32_e32 v35, v32
	s_nop 0
	v_pk_mul_f32 v[32:33], v[48:49], v[34:35] op_sel_hi:[0,1]
	v_pk_mul_f32 v[42:43], v[32:33], v[42:43]
	v_cvt_pk_bf16_f32 v32, v36, v37
	v_mad_i64_i32 v[36:37], s[0:1], v44, s9, v[112:113]
	v_cvt_pk_bf16_f32 v33, v38, v39
	v_cvt_pk_bf16_f32 v34, v40, v41
	v_cvt_pk_bf16_f32 v35, v42, v43
	v_lshl_add_u64 v[36:37], v[36:37], 0, v[114:115]
	global_store_dwordx4 v[36:37], v[32:35], off nt
	s_nop 1
	v_fmamk_f32 v32, v159, 0x3a800000, v235
	v_cmp_gt_f32_e32 vcc, s86, v32
	v_mul_f32_e32 v33, 0x4b800000, v32
	s_nop 0
	v_cndmask_b32_e32 v32, v32, v33, vcc
	v_rsq_f32_e32 v32, v32
	s_nop 0
	v_mul_f32_e32 v33, 0x45800000, v32
	v_cndmask_b32_e32 v32, v32, v33, vcc
	v_mul_f32_e32 v33, 0xbfb8aa3b, v32
	v_mul_f32_e32 v35, v33, v16
	v_exp_f32_e32 v35, v35
	v_mul_f32_e32 v34, v33, v20
	v_exp_f32_e32 v34, v34
	v_mul_f32_e32 v32, v32, v32
	v_add_f32_e32 v35, 1.0, v35
	v_rcp_f32_e32 v36, v35
	v_mul_f32_e32 v35, v33, v21
	v_exp_f32_e32 v35, v35
	v_add_f32_e32 v34, 1.0, v34
	v_rcp_f32_e32 v34, v34
	v_pk_mul_f32 v[20:21], v[20:21], v[28:29]
	v_add_f32_e32 v35, 1.0, v35
	v_rcp_f32_e32 v35, v35
	s_nop 0
	v_pk_mul_f32 v[28:29], v[32:33], v[34:35] op_sel_hi:[0,1]
	v_pk_mul_f32 v[20:21], v[28:29], v[20:21]
	v_mul_f32_e32 v28, v33, v17
	v_exp_f32_e32 v28, v28
	v_pk_mul_f32 v[16:17], v[16:17], v[24:25]
	v_add_f32_e32 v28, 1.0, v28
	v_rcp_f32_e32 v37, v28
	v_add_u32_e32 v28, 0xa0, v154
	v_pk_mul_f32 v[24:25], v[32:33], v[36:37] op_sel_hi:[0,1]
	v_pk_mul_f32 v[24:25], v[24:25], v[16:17]
	v_mul_f32_e32 v17, v33, v18
	v_exp_f32_e32 v17, v17
	v_mul_f32_e32 v16, v33, v22
	v_exp_f32_e32 v16, v16
	v_add_f32_e32 v17, 1.0, v17
	v_rcp_f32_e32 v18, v17
	v_mul_f32_e32 v17, v33, v23
	v_exp_f32_e32 v17, v17
	v_add_f32_e32 v16, 1.0, v16
	v_rcp_f32_e32 v16, v16
	v_add_f32_e32 v17, 1.0, v17
	v_rcp_f32_e32 v17, v17
	s_nop 0
	v_pk_mul_f32 v[16:17], v[32:33], v[16:17] op_sel_hi:[0,1]
	v_pk_mul_f32 v[22:23], v[16:17], v[30:31]
	v_mul_f32_e32 v16, v33, v19
	v_exp_f32_e32 v16, v16
	s_nop 0
	v_add_f32_e32 v16, 1.0, v16
	v_rcp_f32_e32 v19, v16
	s_nop 0
	v_pk_mul_f32 v[16:17], v[32:33], v[18:19] op_sel_hi:[0,1]
	v_pk_mul_f32 v[26:27], v[16:17], v[26:27]
	v_cvt_pk_bf16_f32 v16, v20, v21
	v_mad_i64_i32 v[20:21], s[0:1], v28, s9, v[112:113]
	v_cvt_pk_bf16_f32 v17, v22, v23
	v_cvt_pk_bf16_f32 v18, v24, v25
	v_cvt_pk_bf16_f32 v19, v26, v27
	v_lshl_add_u64 v[20:21], v[20:21], 0, v[114:115]
	global_store_dwordx4 v[20:21], v[16:19], off nt
	s_nop 1
	v_fmamk_f32 v16, v155, 0x3a800000, v235
	v_cmp_gt_f32_e32 vcc, s86, v16
	v_mul_f32_e32 v17, 0x4b800000, v16
	s_nop 0
	v_cndmask_b32_e32 v16, v16, v17, vcc
	v_rsq_f32_e32 v16, v16
	s_nop 0
	v_mul_f32_e32 v17, 0x45800000, v16
	v_cndmask_b32_e32 v16, v16, v17, vcc
	v_mul_f32_e32 v17, 0xbfb8aa3b, v16
	v_mul_f32_e32 v19, v17, v0
	v_exp_f32_e32 v19, v19
	v_mul_f32_e32 v18, v17, v4
	v_exp_f32_e32 v18, v18
	v_mul_f32_e32 v16, v16, v16
	v_add_f32_e32 v19, 1.0, v19
	v_rcp_f32_e32 v20, v19
	v_mul_f32_e32 v19, v17, v5
	v_exp_f32_e32 v19, v19
	v_add_f32_e32 v18, 1.0, v18
	v_rcp_f32_e32 v18, v18
	v_pk_mul_f32 v[4:5], v[4:5], v[12:13]
	v_add_f32_e32 v19, 1.0, v19
	v_rcp_f32_e32 v19, v19
	s_and_b64 vcc, exec, s[38:39]
	v_pk_mul_f32 v[12:13], v[16:17], v[18:19] op_sel_hi:[0,1]
	v_pk_mul_f32 v[4:5], v[12:13], v[4:5]
	v_mul_f32_e32 v12, v17, v1
	v_exp_f32_e32 v12, v12
	v_pk_mul_f32 v[0:1], v[0:1], v[8:9]
	v_add_f32_e32 v12, 1.0, v12
	v_rcp_f32_e32 v21, v12
	v_add_u32_e32 v12, 0xb0, v154
	v_pk_mul_f32 v[8:9], v[16:17], v[20:21] op_sel_hi:[0,1]
	v_pk_mul_f32 v[8:9], v[8:9], v[0:1]
	v_mul_f32_e32 v1, v17, v2
	v_exp_f32_e32 v1, v1
	v_mul_f32_e32 v0, v17, v6
	v_exp_f32_e32 v0, v0
	v_add_f32_e32 v1, 1.0, v1
	v_rcp_f32_e32 v2, v1
	v_mul_f32_e32 v1, v17, v7
	v_exp_f32_e32 v1, v1
	v_add_f32_e32 v0, 1.0, v0
	v_rcp_f32_e32 v0, v0
	v_add_f32_e32 v1, 1.0, v1
	v_rcp_f32_e32 v1, v1
	s_nop 0
	v_pk_mul_f32 v[0:1], v[16:17], v[0:1] op_sel_hi:[0,1]
	v_pk_mul_f32 v[6:7], v[0:1], v[14:15]
	v_mul_f32_e32 v0, v17, v3
	v_exp_f32_e32 v0, v0
	s_nop 0
	v_add_f32_e32 v0, 1.0, v0
	v_rcp_f32_e32 v3, v0
	s_nop 0
	v_pk_mul_f32 v[0:1], v[16:17], v[2:3] op_sel_hi:[0,1]
	v_pk_mul_f32 v[10:11], v[0:1], v[10:11]
	v_cvt_pk_bf16_f32 v0, v4, v5
	v_mad_i64_i32 v[4:5], s[0:1], v12, s9, v[112:113]
	v_cvt_pk_bf16_f32 v1, v6, v7
	v_cvt_pk_bf16_f32 v2, v8, v9
	v_cvt_pk_bf16_f32 v3, v10, v11
	v_lshl_add_u64 v[4:5], v[4:5], 0, v[114:115]
	s_mov_b32 s0, s8
	global_store_dwordx4 v[4:5], v[0:3], off nt
	s_cbranch_vccz .LBB0_388
	s_waitcnt vmcnt(0)
	v_readlane_b32 s20, v255, 27
